# grid barrier: the XCD leader's L1 invalidate is issued together with its cross-XCD arrival atomic instead of after the release condition
# baseline (speedup 1.0000x reference)
.LBB0_668:
	s_or_b64 exec, exec, s[8:9]
	buffer_inv sc1
	s_waitcnt vmcnt(0)
	v_readfirstlane_b32 s6, v2
	v_cvt_f32_u32_e32 v2, v0
	v_sub_u32_e32 v3, 0, v0
	v_add_u32_e32 v1, s6, v1
	v_readlane_b32 s6, v245, 13
	v_rcp_iflag_f32_e32 v2, v2
	v_readlane_b32 s7, v245, 14
	s_mov_b64 s[8:9], -1
	v_mul_f32_e32 v2, 0x4f7ffffe, v2
	v_cvt_u32_f32_e32 v2, v2
	v_mul_lo_u32 v3, v3, v2
	v_mul_hi_u32 v3, v2, v3
	v_add_u32_e32 v2, v2, v3
	v_mul_hi_u32 v2, v1, v2
	v_mul_lo_u32 v3, v2, v0
	v_sub_u32_e32 v3, v1, v3
	v_cmp_ge_u32_e32 vcc, v3, v0
	v_add_u32_e32 v4, 1, v2
	v_add_u32_e32 v1, 1, v1
	v_cndmask_b32_e32 v2, v2, v4, vcc
	v_sub_u32_e32 v4, v3, v0
	v_cndmask_b32_e32 v3, v3, v4, vcc
	v_cmp_ge_u32_e32 vcc, v3, v0
	v_add_u32_e32 v3, 1, v2
	s_nop 0
	v_cndmask_b32_e32 v2, v2, v3, vcc
	v_mul_lo_u32 v3, v0, v2
	v_add_u32_e32 v0, v3, v0
	v_cmp_ne_u32_e32 vcc, v1, v0
	v_mov_b32_e32 v4, v0
	v_mov_b64_e32 v[0:1], s[6:7]
	s_and_saveexec_b64 s[6:7], vcc
	s_cbranch_execz .LBB0_680
	v_readlane_b32 s8, v245, 11
	v_readlane_b32 s9, v245, 12
	s_mov_b64 s[10:11], 0
	s_nop 3
	global_load_dword v0, v137, s[8:9] sc1
	s_waitcnt vmcnt(0)
	v_cmp_lt_u32_e32 vcc, v0, v4
	s_and_saveexec_b64 s[8:9], vcc
	s_cbranch_execz .LBB0_679
	s_mov_b32 s20, 1
	s_branch .LBB0_672

.LBB0_682:
	s_or_b64 exec, exec, s[6:7]
	s_mov_b64 s[6:7], exec
	v_mbcnt_lo_u32_b32 v0, s6, 0
	v_mbcnt_hi_u32_b32 v0, s7, v0
	v_cmp_eq_u32_e32 vcc, 0, v0
	s_waitcnt vmcnt(0)
	s_and_saveexec_b64 s[8:9], vcc
	s_cbranch_execz .LBB0_684
	s_bcnt1_i32_b64 s6, s[6:7]
	v_mov_b32_e32 v0, s6
	v_readlane_b32 s6, v245, 9
	v_readlane_b32 s7, v245, 10
	s_nop 4
	global_atomic_add v137, v0, s[6:7]
